# attention: K/V staging pointers constant per phase, per-tile advance by VGPR offsets (3 VALU instead of 14 SALU), bases computed once
# baseline (speedup 1.0000x reference)
.LBB0_316:
	v_readlane_b32 s4, v251, 48
	v_readlane_b32 s34, v253, 15
	v_mbcnt_lo_u32_b32 v0, -1, 0
	v_mbcnt_hi_u32_b32 v0, -1, v0
	s_lshr_b32 s36, s4, 2
	s_and_b32 s31, s4, 3
	s_lshr_b32 s29, s36, 3
	s_and_b32 s30, s36, 7
	s_lshr_b32 s34, s34, 6
	s_lshr_b32 s35, s34, 2
	v_and_b32_e32 v240, 31, v0
	v_lshrrev_b32_e32 v241, 5, v0
	v_lshl_add_u32 v247, s34, 6, v0
	v_lshrrev_b32_e32 v248, 4, v247
	v_and_b32_e32 v249, 15, v247
	v_lshlrev_b32_e32 v220, 11, v248
	v_lshl_add_u32 v220, v249, 4, v220
	v_mul_u32_u24_e32 v225, 0x190, v248
	v_lshl_add_u32 v225, v249, 4, v225
	v_lshrrev_b32_e32 v248, 3, v247
	v_and_b32_e32 v249, 7, v247
	v_lshlrev_b32_e32 v221, 7, v248
	v_lshl_add_u32 v221, v249, 4, v221
	v_mul_u32_u24_e32 v226, 0x190, v248
	v_lshl_add_u32 v226, v249, 4, v226
	v_add_u32_e32 v226, 0x100, v226
	v_mul_u32_u24_e32 v222, 0x8200, v248
	v_lshl_add_u32 v222, v249, 4, v222
	v_mul_u32_u24_e32 v227, 0x88, v248
	v_lshl_add_u32 v227, v249, 4, v227
	v_add_u32_e32 v227, 0x12c00, v227
	v_add_u32_e32 v228, 0x2200, v227
	v_lshlrev_b32_e32 v229, 2, v0
	v_add_u32_e32 v229, 0x1f800, v229
	v_mul_u32_u24_e32 v230, 0x190, v240
	v_lshl_add_u32 v230, v241, 4, v230
	v_mul_u32_u24_e32 v231, 0x88, v240
	v_lshl_add_u32 v231, v241, 3, v231
	v_add_u32_e32 v231, 0x12c00, v231
	v_lshlrev_b32_e32 v232, 4, v241
	v_add_u32_e32 v232, 0x1f800, v232
	v_xor_b32_e32 v233, 32, v0
	v_lshlrev_b32_e32 v233, 2, v233
	v_mov_b32_e32 v238, 0xf149f2ca
	s_mov_b32 s26, 0
	s_mul_i32 s38, s29, 0x810
	s_mul_i32 s36, s30, 0x180
	s_add_u32 s40, s50, s36
	s_addc_u32 s41, s51, 0
	s_lshl_b32 s36, s30, 8
	s_add_u32 s36, s36, 0xc380000
	s_add_u32 s6, s48, s36
	s_addc_u32 s7, s49, 0
	s_lshl_b32 s73, s38, 11
	s_add_u32 s72, s73, 0x10480000
	s_lshl_b32 s73, s30, 8
	s_add_u32 s72, s72, s73
	s_add_u32 s8, s48, s72
	s_addc_u32 s9, s49, 0
	s_add_u32 s10, s8, 0x10000
	s_addc_u32 s11, s9, 0
	s_lshl_b32 s73, s38, 7
	s_add_u32 s72, s73, 0x14da0000
	s_add_u32 s12, s48, s72
	s_addc_u32 s13, s49, 0
	s_mul_i32 s73, s30, 0x410000
	s_lshl_b32 s72, s38, 1
	s_add_u32 s72, s72, s73
	s_add_u32 s72, s72, 0x12500000
	s_add_u32 s14, s48, s72
	s_addc_u32 s15, s49, 0
	s_add_u32 s16, s14, 0x208000
	s_addc_u32 s17, s15, 0
	s_lshl_b32 s73, s38, 5
	s_add_u32 s72, s73, 0x150fc400
	s_lshl_b32 s73, s30, 2
	s_add_u32 s72, s72, s73
	s_add_u32 s18, s48, s72
	s_addc_u32 s19, s49, 0
	s_lshl_b32 s73, s38, 2
	s_add_u32 s72, s73, 0x1506a000
	s_add_u32 s20, s48, s72
	s_addc_u32 s21, s49, 0
.Lat_item:
	s_sub_i32 s36, 8, s31
	s_add_i32 s37, s31, 1
	s_cmp_eq_u32 s26, 0
	s_cselect_b32 s36, s36, s37
	s_cmp_eq_u32 s26, 2
	s_cselect_b32 s36, 0, s36
	s_lshl_b32 s27, s36, 8
	s_sub_i32 s27, s27, 0xf0
	s_cmp_eq_u32 s36, 0
	s_cselect_b32 s27, 0, s27
	s_cselect_b32 s28, 16, 0x100
	s_add_i32 s23, s27, s28
	s_add_i32 s23, s23, 63
	s_lshr_b32 s23, s23, 6
	s_lshl_b32 s65, s34, 5
	s_add_i32 s64, s65, s27
	s_add_i32 s25, s64, 31
	s_lshr_b32 s25, s25, 6
	s_cmp_lt_u32 s65, s28
	s_cselect_b32 s25, s25, -1
	v_add_u32_e32 v234, s64, v240
	v_lshlrev_b32_e32 v0, 2, v241
	v_sub_u32_e32 v239, v234, v0
	s_cmp_lg_u32 s26, 0
	s_cbranch_scc1 .Lat_item_nofetch
	s_mov_b32 s4, s27
	s_lshl_b32 s65, s34, 5
	s_add_i32 s5, s65, s4
	v_add_u32_e32 v0, s5, v240
	v_min_u32_e32 v0, 0x80f, v0
	v_add_u32_e32 v0, s38, v0
	s_movk_i32 s39, 0xc00
	v_mul_lo_u32 v247, v0, s39
	v_lshl_add_u32 v247, v241, 4, v247
	v_lshlrev_b32_e32 v242, 5, v0
	global_load_dwordx4 v[98:101], v247, s[40:41]
	global_load_dwordx4 v[102:105], v247, s[40:41] offset:32
	global_load_dwordx4 v[106:109], v247, s[40:41] offset:64
	global_load_dwordx4 v[110:113], v247, s[40:41] offset:96
	global_load_dwordx4 v[114:117], v247, s[40:41] offset:128
	global_load_dwordx4 v[118:121], v247, s[40:41] offset:160
	global_load_dwordx4 v[122:125], v247, s[40:41] offset:192
	global_load_dwordx4 v[126:129], v247, s[40:41] offset:224
	global_load_dwordx4 v[130:133], v247, s[40:41] offset:256
	global_load_dwordx4 v[134:137], v247, s[40:41] offset:288
	global_load_dwordx4 v[138:141], v247, s[40:41] offset:320
	global_load_dwordx4 v[142:145], v247, s[40:41] offset:352
	s_lshl_b32 s36, s30, 2
	s_add_u32 s36, s36, 0x1507a400
	s_add_u32 s36, s48, s36
	s_addc_u32 s37, s49, 0
	global_load_dword v249, v242, s[36:37]
	v_lshl_add_u32 v0, v241, 5, v240
	v_lshl_add_u32 v0, s34, 6, v0
	v_lshrrev_b32_e32 v247, 4, v0
	v_and_b32_e32 v242, 15, v0
	v_lshlrev_b32_e32 v220, 11, v247
	v_lshl_add_u32 v220, v242, 4, v220
	v_lshrrev_b32_e32 v247, 3, v0
	v_and_b32_e32 v242, 7, v0
	v_lshlrev_b32_e32 v221, 7, v247
	v_lshl_add_u32 v221, v242, 4, v221
	v_mul_u32_u24_e32 v222, 0x8200, v247
	v_lshl_add_u32 v222, v242, 4, v222
	s_mov_b32 s97, 0
	global_load_dwordx4 v[198:201], v220, s[8:9]
	global_load_dwordx4 v[202:205], v220, s[10:11]
	global_load_dwordx4 v[206:209], v221, s[12:13]
	global_load_dwordx4 v[210:213], v222, s[14:15]
	global_load_dwordx4 v[214:217], v222, s[16:17]
	s_cmp_lg_u32 s34, 0
	s_cbranch_scc1 .Lat_nosq1
	v_lshl_add_u32 v247, v241, 5, v240
	v_lshl_add_u32 v247, s97, 6, v247
	v_lshlrev_b32_e32 v242, 2, v247
	v_lshlrev_b32_e32 v247, 5, v247
	global_load_dword v218, v247, s[18:19]
	global_load_dword v219, v242, s[20:21]

.Lat_item_nobar:
	s_cmp_lt_u32 s23, 2
	s_cbranch_scc1 .Lat_h_one
	v_add_u32_e32 v220, 0x20000, v220
	v_add_u32_e32 v221, 0x2000, v221
	v_add_u32_e32 v222, 0x80, v222
	s_add_i32 s97, s97, 1
	global_load_dwordx4 v[146:149], v220, s[8:9]
	global_load_dwordx4 v[150:153], v220, s[10:11]
	global_load_dwordx4 v[154:157], v221, s[12:13]
	global_load_dwordx4 v[158:161], v222, s[14:15]
	global_load_dwordx4 v[194:197], v222, s[16:17]
	s_cmp_lg_u32 s34, 0
	s_cbranch_scc1 .Lat_nosq2
	v_lshl_add_u32 v247, v241, 5, v240
	v_lshl_add_u32 v247, s97, 6, v247
	v_lshlrev_b32_e32 v242, 2, v247
	v_lshlrev_b32_e32 v247, 5, v247
	global_load_dword v223, v247, s[18:19]
	global_load_dword v224, v242, s[20:21]

.Lat_nosc5:
	v_mov_b32_e32 v242, 0x358637bd
	v_fmamk_f32 v235, v249, 0x3baaaaab, v242
	v_rsq_f32_e32 v235, v235
	s_nop 0
	v_mul_f32_e32 v235, 0x3dd53b95, v235
	s_cmp_lt_u32 s23, 3
	s_cbranch_scc1 .Lat_no_t2
	v_add_u32_e32 v220, 0x20000, v220
	v_add_u32_e32 v221, 0x2000, v221
	v_add_u32_e32 v222, 0x80, v222
	s_add_i32 s97, s97, 1
	global_load_dwordx4 v[198:201], v220, s[8:9]
	global_load_dwordx4 v[202:205], v220, s[10:11]
	global_load_dwordx4 v[206:209], v221, s[12:13]
	global_load_dwordx4 v[210:213], v222, s[14:15]
	global_load_dwordx4 v[214:217], v222, s[16:17]
	s_cmp_lg_u32 s34, 0
	s_cbranch_scc1 .Lat_nosq6
	v_lshl_add_u32 v247, v241, 5, v240
	v_lshl_add_u32 v247, s97, 6, v247
	v_lshlrev_b32_e32 v242, 2, v247
	v_lshlrev_b32_e32 v247, 5, v247
	global_load_dword v218, v247, s[18:19]
	global_load_dword v219, v242, s[20:21]

.Lat_nosc9:
	s_add_i32 s65, s22, 3
	s_cmp_ge_u32 s65, s23
	s_cbranch_scc1 .Lat_x_nostore
	v_add_u32_e32 v220, 0x20000, v220
	v_add_u32_e32 v221, 0x2000, v221
	v_add_u32_e32 v222, 0x80, v222
	s_add_i32 s97, s97, 1
	global_load_dwordx4 v[198:201], v220, s[8:9]
	global_load_dwordx4 v[202:205], v220, s[10:11]
	global_load_dwordx4 v[206:209], v221, s[12:13]
	global_load_dwordx4 v[210:213], v222, s[14:15]
	global_load_dwordx4 v[214:217], v222, s[16:17]
	s_cmp_lg_u32 s34, 0
	s_cbranch_scc1 .Lat_nosq10
	v_lshl_add_u32 v247, v241, 5, v240
	v_lshl_add_u32 v247, s97, 6, v247
	v_lshlrev_b32_e32 v242, 2, v247
	v_lshlrev_b32_e32 v247, 5, v247
	global_load_dword v218, v247, s[18:19]
	global_load_dword v219, v242, s[20:21]

.Lat_nosc11:
	s_add_i32 s65, s22, 3
	s_cmp_ge_u32 s65, s23
	s_cbranch_scc1 .Lat_x_nostore
	v_add_u32_e32 v220, 0x20000, v220
	v_add_u32_e32 v221, 0x2000, v221
	v_add_u32_e32 v222, 0x80, v222
	s_add_i32 s97, s97, 1
	global_load_dwordx4 v[146:149], v220, s[8:9]
	global_load_dwordx4 v[150:153], v220, s[10:11]
	global_load_dwordx4 v[154:157], v221, s[12:13]
	global_load_dwordx4 v[158:161], v222, s[14:15]
	global_load_dwordx4 v[194:197], v222, s[16:17]
	s_cmp_lg_u32 s34, 0
	s_cbranch_scc1 .Lat_nosq12
	v_lshl_add_u32 v247, v241, 5, v240
	v_lshl_add_u32 v247, s97, 6, v247
	v_lshlrev_b32_e32 v242, 2, v247
	v_lshlrev_b32_e32 v247, 5, v247
	global_load_dword v223, v247, s[18:19]
	global_load_dword v224, v242, s[20:21]

.Lat_x_pf:
	s_lshl_b32 s65, s34, 5
	s_add_i32 s5, s65, s4
	v_add_u32_e32 v0, s5, v240
	v_min_u32_e32 v0, 0x80f, v0
	v_add_u32_e32 v0, s38, v0
	s_movk_i32 s39, 0xc00
	v_mul_lo_u32 v247, v0, s39
	v_lshl_add_u32 v247, v241, 4, v247
	v_lshlrev_b32_e32 v242, 5, v0
	global_load_dwordx4 v[98:101], v247, s[40:41]
	global_load_dwordx4 v[102:105], v247, s[40:41] offset:32
	global_load_dwordx4 v[106:109], v247, s[40:41] offset:64
	global_load_dwordx4 v[110:113], v247, s[40:41] offset:96
	global_load_dwordx4 v[114:117], v247, s[40:41] offset:128
	global_load_dwordx4 v[118:121], v247, s[40:41] offset:160
	global_load_dwordx4 v[122:125], v247, s[40:41] offset:192
	global_load_dwordx4 v[126:129], v247, s[40:41] offset:224
	global_load_dwordx4 v[130:133], v247, s[40:41] offset:256
	global_load_dwordx4 v[134:137], v247, s[40:41] offset:288
	global_load_dwordx4 v[138:141], v247, s[40:41] offset:320
	global_load_dwordx4 v[142:145], v247, s[40:41] offset:352
	s_lshl_b32 s36, s30, 2
	s_add_u32 s36, s36, 0x1507a400
	s_add_u32 s36, s48, s36
	s_addc_u32 s37, s49, 0
	global_load_dword v249, v242, s[36:37]
	v_lshl_add_u32 v0, v241, 5, v240
	v_lshl_add_u32 v0, s34, 6, v0
	v_lshrrev_b32_e32 v247, 4, v0
	v_and_b32_e32 v242, 15, v0
	v_lshlrev_b32_e32 v220, 11, v247
	v_lshl_add_u32 v220, v242, 4, v220
	v_lshrrev_b32_e32 v247, 3, v0
	v_and_b32_e32 v242, 7, v0
	v_lshlrev_b32_e32 v221, 7, v247
	v_lshl_add_u32 v221, v242, 4, v221
	v_mul_u32_u24_e32 v222, 0x8200, v247
	v_lshl_add_u32 v222, v242, 4, v222
	s_mov_b32 s97, 0
	global_load_dwordx4 v[198:201], v220, s[8:9]
	global_load_dwordx4 v[202:205], v220, s[10:11]
	global_load_dwordx4 v[206:209], v221, s[12:13]
	global_load_dwordx4 v[210:213], v222, s[14:15]
	global_load_dwordx4 v[214:217], v222, s[16:17]
	s_cmp_lg_u32 s34, 0
	s_cbranch_scc1 .Lat_nosq13
	v_lshl_add_u32 v247, v241, 5, v240
	v_lshl_add_u32 v247, s97, 6, v247
	v_lshlrev_b32_e32 v242, 2, v247
	v_lshlrev_b32_e32 v247, 5, v247
	global_load_dword v218, v247, s[18:19]
	global_load_dword v219, v242, s[20:21]
